# v24 + GEMM K-loop back edge rotated: pointer updates, exit test and next-iteration scalar set-up moved in front of the loop-back barrier
# baseline (speedup 1.0000x reference)
; #define PG8_STAGE(bufoff, gbase, voff) do { _Pragma("unroll") for (int _i = 0; _i < 2; ++_i) \
;         __builtin_amdgcn_global_load_lds((const unsigned*)((const char*)(gbase) + (voff)[_i]), (PG8_LAS unsigned*)(lds + (bufoff) + ldsw + _i * 8192), 16, 0, 0); } while (0)
; #define PG8_LDA(dst, b, h) do { _Pragma("unroll") for (int m = 0; m < 4; ++m) _Pragma("unroll") for (int k = 0; k < 2; ++k) dst[m][k] = *(const PG8_LAS bf16x8*)(lds + PG8_SA(b, h) + aoff + m * 2048 + k * 1024); } while (0)
; #define PG8_LDB(dst, b, h) do { _Pragma("unroll") for (int n = 0; n < 2; ++n) _Pragma("unroll") for (int k = 0; k < 2; ++k) dst[n][k] = *(const PG8_LAS bf16x8*)(lds + PG8_SB(b, h) + boff + n * 2048 + k * 1024); } while (0)
; #define PG8_WAIT_V(n) asm volatile("s_waitcnt vmcnt(" #n ")" ::: "memory")
; #define PG8_WAIT_L(n) asm volatile("s_waitcnt lgkmcnt(" #n ")" ::: "memory")
; #define PG8_BAR __builtin_amdgcn_s_barrier()
; #define PG8_SCHED __builtin_amdgcn_sched_barrier(0)
; template <class Epi, class Sched, bool ALIGN_EPI = false, bool SP2 = false>
; __device__ __forceinline__ void gemm_phase(PG8_LAS unsigned char* lds, const Gemm g, const Sched& S, const Epi& E) {
;     ...
;         const bool has_next = S.next(ui + 1, nxt);
;         const char* nA = has_next ? (const char*)g.A + (size_t)nxt.pm * tstep : cA; const char* nB = has_next ? (const char*)g.Bt + (size_t)nxt.pn * tstep : cB;
;         for (int t = 0; t < nt; t += 2) {
;             const bool last = (t == nt - 2);
;             const char* a1 = cA + (size_t)(t + 1) * kstep;
;             const char* a2 = last ? nA : cA + (size_t)(t + 2) * kstep; const char* b2 = last ? nB : cB + (size_t)(t + 2) * kstep;
;             const char* a3 = a2 + kstep; const char* b3 = b2 + kstep;
;             if (last && has_next) S.a_ready(nxt);
;             if constexpr (SP2) {
;             PG8_LDB(B0, 0, 0); PG8_LDB(B1, 0, 1); PG8_SCHED; PG8_LDA(At, 0, 0); PG8_STAGE(PG8_SA(1, 1), a1 + hstep, voffA);
;             PG8_WAIT_V(8); PG8_WAIT_L(0); PG8_BAR; PG8_MMA(0, 0, At, B0); PG8_MMA(0, 1, At, B1); PG8_BAR; PG8_SCHED;
;             PG8_LDA(At, 0, 1); PG8_STAGE(PG8_SB(0, 0), b2, voffB); PG8_STAGE(PG8_SB(0, 1), b2 + hstep, voffB); PG8_STAGE(PG8_SA(0, 0), a2, voffA);
;             PG8_WAIT_V(8); PG8_WAIT_L(0); PG8_BAR; PG8_MMA(1, 0, At, B0); PG8_MMA(1, 1, At, B1); PG8_BAR; PG8_SCHED;
.LBB0_687:
	s_add_u32 s8, s8, 0x80
	s_addc_u32 s9, s9, 0
	s_add_u32 s27, s16, 0x100
	s_addc_u32 s30, s17, 0
	s_mov_b32 s16, 0
	s_waitcnt lgkmcnt(0)
	s_waitcnt lgkmcnt(0)
	s_add_i32 s31, s16, 2
	s_add_u32 s36, s8, 0x80
	s_addc_u32 s17, s9, 0
	s_add_i32 s41, 0, 0x10000
	s_cmp_eq_u32 s72, s16
	s_cselect_b32 s17, s1, s17
	s_cselect_b32 s16, s0, s36
	s_cselect_b32 vcc_hi, s93, s30
	s_cselect_b32 vcc_lo, s92, s27
	s_add_i32 s36, 0, 0x14000
	v_add_u32_e32 v152, s41, v161
	v_add_u32_e32 v178, s36, v161
	ds_read_b128 v[140:143], v152
	ds_read_b128 v[144:147], v152 offset:1024
	ds_read_b128 v[148:151], v152 offset:2048
	ds_read_b128 v[152:155], v152 offset:3072
	ds_read_b128 v[156:159], v178
	ds_read_b128 v[170:173], v178 offset:1024
	ds_read_b128 v[174:177], v178 offset:2048
	ds_read_b128 v[178:181], v178 offset:3072
	v_lshl_add_u64 v[210:211], s[8:9], 0, v[136:137]
	s_add_i32 m0, s76, 0xc000
	ds_read_b128 v[182:185], v169
	ds_read_b128 v[186:189], v169 offset:1024
	ds_read_b128 v[190:193], v169 offset:2048
	ds_read_b128 v[194:197], v169 offset:3072
	ds_read_b128 v[198:201], v169 offset:4096
	ds_read_b128 v[202:205], v169 offset:5120
	ds_read_b128 v[206:209], v169 offset:6144
	ds_read_b128 v[230:233], v169 offset:7168
	global_load_lds_dwordx4 v[210:211], off
	v_lshl_add_u64 v[210:211], s[8:9], 0, v[138:139]
	s_add_i32 m0, s76, 0xe000
	s_nop 0
	global_load_lds_dwordx4 v[210:211], off
	s_waitcnt vmcnt(8)
	s_waitcnt lgkmcnt(0)
	s_barrier
	s_setprio 1
	s_waitcnt lgkmcnt(0)
	v_mfma_f32_16x16x32_bf16 v[126:129], v[140:143], v[182:185], 0
	v_mfma_f32_16x16x32_bf16 v[122:125], v[148:151], v[182:185], 0
	v_mfma_f32_16x16x32_bf16 v[110:113], v[140:143], v[190:193], 0
	v_mfma_f32_16x16x32_bf16 v[106:109], v[148:151], v[190:193], 0
	v_mfma_f32_16x16x32_bf16 v[94:97], v[140:143], v[198:201], 0
	v_mfma_f32_16x16x32_bf16 v[90:93], v[148:151], v[198:201], 0
	v_mfma_f32_16x16x32_bf16 v[78:81], v[140:143], v[206:209], 0
	v_mfma_f32_16x16x32_bf16 v[74:77], v[148:151], v[206:209], 0
	v_mfma_f32_16x16x32_bf16 v[126:129], v[144:147], v[186:189], v[126:129]
	v_mfma_f32_16x16x32_bf16 v[122:125], v[152:155], v[186:189], v[122:125]
	v_mfma_f32_16x16x32_bf16 v[110:113], v[144:147], v[194:197], v[110:113]
	v_mfma_f32_16x16x32_bf16 v[106:109], v[152:155], v[194:197], v[106:109]
	v_mfma_f32_16x16x32_bf16 v[94:97], v[144:147], v[202:205], v[94:97]
	v_mfma_f32_16x16x32_bf16 v[90:93], v[152:155], v[202:205], v[90:93]
	v_mfma_f32_16x16x32_bf16 v[78:81], v[144:147], v[230:233], v[78:81]
	v_mfma_f32_16x16x32_bf16 v[74:77], v[152:155], v[230:233], v[74:77]
	s_setprio 0
	s_setprio 1
	v_mfma_f32_16x16x32_bf16 v[118:121], v[156:159], v[182:185], 0
	v_mfma_f32_16x16x32_bf16 v[114:117], v[174:177], v[182:185], 0
	v_mfma_f32_16x16x32_bf16 v[102:105], v[156:159], v[190:193], 0
	v_mfma_f32_16x16x32_bf16 v[98:101], v[174:177], v[190:193], 0
	v_mfma_f32_16x16x32_bf16 v[86:89], v[156:159], v[198:201], 0
	v_mfma_f32_16x16x32_bf16 v[82:85], v[174:177], v[198:201], 0
	v_mfma_f32_16x16x32_bf16 v[70:73], v[156:159], v[206:209], 0
	v_mfma_f32_16x16x32_bf16 v[66:69], v[174:177], v[206:209], 0
	v_mfma_f32_16x16x32_bf16 v[118:121], v[170:173], v[186:189], v[118:121]
	v_mfma_f32_16x16x32_bf16 v[114:117], v[178:181], v[186:189], v[114:117]
	v_mfma_f32_16x16x32_bf16 v[102:105], v[170:173], v[194:197], v[102:105]
	v_mfma_f32_16x16x32_bf16 v[98:101], v[178:181], v[194:197], v[98:101]
	v_mfma_f32_16x16x32_bf16 v[86:89], v[170:173], v[202:205], v[86:89]
	v_mfma_f32_16x16x32_bf16 v[82:85], v[178:181], v[202:205], v[82:85]
	v_mfma_f32_16x16x32_bf16 v[70:73], v[170:173], v[230:233], v[70:73]
	v_mfma_f32_16x16x32_bf16 v[66:69], v[178:181], v[230:233], v[66:69]
	s_setprio 0
	s_barrier
	s_add_i32 s41, s41, s65
	v_lshl_add_u64 v[210:211], vcc, 0, v[64:65]
	s_mov_b32 m0, s41
	ds_read_b128 v[182:185], v169 offset:16384
	ds_read_b128 v[186:189], v169 offset:17408
	ds_read_b128 v[190:193], v169 offset:18432
	ds_read_b128 v[194:197], v169 offset:19456
	ds_read_b128 v[198:201], v169 offset:20480
	ds_read_b128 v[202:205], v169 offset:21504
	ds_read_b128 v[206:209], v169 offset:22528
	ds_read_b128 v[230:233], v169 offset:23552
	global_load_lds_dwordx4 v[210:211], off
	s_add_i32 m0, s41, 0x2000
	v_lshl_add_u64 v[234:235], vcc, 0, v[134:135]
	s_add_u32 vcc_lo, vcc_lo, s4
	s_addc_u32 vcc_hi, vcc_hi, 0
	s_add_i32 s36, s36, s65
	global_load_lds_dwordx4 v[234:235], off
	v_lshl_add_u64 v[236:237], vcc, 0, v[64:65]
	s_mov_b32 m0, s36
	v_lshl_add_u64 v[238:239], vcc, 0, v[134:135]
	global_load_lds_dwordx4 v[236:237], off
	s_add_i32 m0, s36, 0x2000
	v_lshl_add_u64 v[244:245], s[16:17], 0, v[130:131]
	global_load_lds_dwordx4 v[238:239], off
	s_mov_b32 m0, s76
	v_lshl_add_u64 v[246:247], s[16:17], 0, v[132:133]
	global_load_lds_dwordx4 v[244:245], off
	s_mov_b32 m0, s2
	s_nop 0
	global_load_lds_dwordx4 v[246:247], off
	s_waitcnt vmcnt(8)
	s_waitcnt lgkmcnt(0)
	s_barrier
; #define PG8_STAGE(bufoff, gbase, voff) do { _Pragma("unroll") for (int _i = 0; _i < 2; ++_i) \
;         __builtin_amdgcn_global_load_lds((const unsigned*)((const char*)(gbase) + (voff)[_i]), (PG8_LAS unsigned*)(lds + (bufoff) + ldsw + _i * 8192), 16, 0, 0); } while (0)
; #define PG8_LDA(dst, b, h) do { _Pragma("unroll") for (int m = 0; m < 4; ++m) _Pragma("unroll") for (int k = 0; k < 2; ++k) dst[m][k] = *(const PG8_LAS bf16x8*)(lds + PG8_SA(b, h) + aoff + m * 2048 + k * 1024); } while (0)
; #define PG8_LDB(dst, b, h) do { _Pragma("unroll") for (int n = 0; n < 2; ++n) _Pragma("unroll") for (int k = 0; k < 2; ++k) dst[n][k] = *(const PG8_LAS bf16x8*)(lds + PG8_SB(b, h) + boff + n * 2048 + k * 1024); } while (0)
; #define PG8_MMA(ai, bj, At, Bt) do { __builtin_amdgcn_s_setprio(1); _Pragma("unroll") for (int m = 0; m < 4; ++m) _Pragma("unroll") for (int n = 0; n < 2; ++n) _Pragma("unroll") for (int k = 0; k < 2; ++k) \
;         acc[ai][bj][m][n] = __builtin_amdgcn_mfma_f32_16x16x32_bf16(Bt[n][k], At[m][k], acc[ai][bj][m][n], 0, 0, 0); __builtin_amdgcn_s_setprio(0); } while (0)
; #define PG8_WAIT_V(n) asm volatile("s_waitcnt vmcnt(" #n ")" ::: "memory")
; #define PG8_WAIT_L(n) asm volatile("s_waitcnt lgkmcnt(" #n ")" ::: "memory")
; #define PG8_BAR __builtin_amdgcn_s_barrier()
; #define PG8_SCHED __builtin_amdgcn_sched_barrier(0)
; template <class Epi, class Sched, bool ALIGN_EPI = false, bool SP2 = false>
; __device__ __forceinline__ void gemm_phase(PG8_LAS unsigned char* lds, const Gemm g, const Sched& S, const Epi& E) {
;     ...
;             PG8_WAIT_V(8); PG8_WAIT_L(0); PG8_BAR; PG8_MMA(1, 0, At, B0); PG8_MMA(1, 1, At, B1); PG8_BAR; PG8_SCHED;
;             PG8_LDB(B0, 1, 0); PG8_LDB(B1, 1, 1); PG8_SCHED; PG8_LDA(At, 1, 0); PG8_STAGE(PG8_SA(0, 1), a2 + hstep, voffA);
;             PG8_WAIT_V(8); PG8_WAIT_L(0); PG8_BAR; PG8_MMA(0, 0, At, B0); PG8_MMA(0, 1, At, B1); PG8_BAR; PG8_SCHED;
	s_setprio 1
	s_waitcnt lgkmcnt(0)
	v_mfma_f32_16x16x32_bf16 v[60:63], v[140:143], v[182:185], 0
	v_mfma_f32_16x16x32_bf16 v[56:59], v[148:151], v[182:185], 0
	v_mfma_f32_16x16x32_bf16 v[44:47], v[140:143], v[190:193], 0
	v_mfma_f32_16x16x32_bf16 v[40:43], v[148:151], v[190:193], 0
	v_mfma_f32_16x16x32_bf16 v[28:31], v[140:143], v[198:201], 0
	v_mfma_f32_16x16x32_bf16 v[24:27], v[148:151], v[198:201], 0
	v_mfma_f32_16x16x32_bf16 v[12:15], v[140:143], v[206:209], 0
	v_mfma_f32_16x16x32_bf16 v[8:11], v[148:151], v[206:209], 0
	v_mfma_f32_16x16x32_bf16 v[60:63], v[144:147], v[186:189], v[60:63]
	v_mfma_f32_16x16x32_bf16 v[56:59], v[152:155], v[186:189], v[56:59]
	v_mfma_f32_16x16x32_bf16 v[44:47], v[144:147], v[194:197], v[44:47]
	v_mfma_f32_16x16x32_bf16 v[40:43], v[152:155], v[194:197], v[40:43]
	v_mfma_f32_16x16x32_bf16 v[28:31], v[144:147], v[202:205], v[28:31]
	v_mfma_f32_16x16x32_bf16 v[24:27], v[152:155], v[202:205], v[24:27]
	v_mfma_f32_16x16x32_bf16 v[12:15], v[144:147], v[230:233], v[12:15]
	v_mfma_f32_16x16x32_bf16 v[8:11], v[152:155], v[230:233], v[8:11]
	s_setprio 0
	s_setprio 1
	v_mfma_f32_16x16x32_bf16 v[52:55], v[156:159], v[182:185], 0
	v_mfma_f32_16x16x32_bf16 v[48:51], v[174:177], v[182:185], 0
	v_mfma_f32_16x16x32_bf16 v[36:39], v[156:159], v[190:193], 0
	v_mfma_f32_16x16x32_bf16 v[32:35], v[174:177], v[190:193], 0
	v_mfma_f32_16x16x32_bf16 v[20:23], v[156:159], v[198:201], 0
	v_mfma_f32_16x16x32_bf16 v[16:19], v[174:177], v[198:201], 0
	v_mfma_f32_16x16x32_bf16 v[4:7], v[156:159], v[206:209], 0
	v_mfma_f32_16x16x32_bf16 v[0:3], v[174:177], v[206:209], 0
	v_mfma_f32_16x16x32_bf16 v[52:55], v[170:173], v[186:189], v[52:55]
	v_mfma_f32_16x16x32_bf16 v[48:51], v[178:181], v[186:189], v[48:51]
	v_mfma_f32_16x16x32_bf16 v[36:39], v[170:173], v[194:197], v[36:39]
	v_mfma_f32_16x16x32_bf16 v[32:35], v[178:181], v[194:197], v[32:35]
	v_mfma_f32_16x16x32_bf16 v[20:23], v[170:173], v[202:205], v[20:23]
	v_mfma_f32_16x16x32_bf16 v[16:19], v[178:181], v[202:205], v[16:19]
	v_mfma_f32_16x16x32_bf16 v[4:7], v[170:173], v[230:233], v[4:7]
	v_mfma_f32_16x16x32_bf16 v[0:3], v[178:181], v[230:233], v[0:3]
	s_setprio 0
	s_barrier
	s_add_i32 s36, 0, 0x18000
	s_add_i32 s41, 0, 0x1c000
	v_add_u32_e32 v152, s36, v161
	v_add_u32_e32 v178, s41, v161
	ds_read_b128 v[140:143], v152
	ds_read_b128 v[144:147], v152 offset:1024
	ds_read_b128 v[148:151], v152 offset:2048
	ds_read_b128 v[152:155], v152 offset:3072
	ds_read_b128 v[156:159], v178
	ds_read_b128 v[170:173], v178 offset:1024
	ds_read_b128 v[174:177], v178 offset:2048
	ds_read_b128 v[178:181], v178 offset:3072
	s_add_u32 s16, s16, s4
	s_addc_u32 s17, s17, 0
	s_mov_b32 m0, s3
	v_lshl_add_u64 v[248:249], s[16:17], 0, v[130:131]
	ds_read_b128 v[182:185], v169 offset:32768
	ds_read_b128 v[186:189], v169 offset:33792
	ds_read_b128 v[190:193], v169 offset:34816
	ds_read_b128 v[194:197], v169 offset:35840
	ds_read_b128 v[198:201], v169 offset:36864
	ds_read_b128 v[202:205], v169 offset:37888
	ds_read_b128 v[206:209], v169 offset:38912
	ds_read_b128 v[230:233], v169 offset:39936
	global_load_lds_dwordx4 v[248:249], off
	v_lshl_add_u64 v[248:249], s[16:17], 0, v[132:133]
	s_mov_b32 m0, s70
	s_nop 0
	global_load_lds_dwordx4 v[248:249], off
	s_waitcnt vmcnt(8)
	s_waitcnt lgkmcnt(0)
	s_barrier
	s_setprio 1
	s_waitcnt lgkmcnt(0)
	v_mfma_f32_16x16x32_bf16 v[126:129], v[140:143], v[182:185], v[126:129]
	v_mfma_f32_16x16x32_bf16 v[122:125], v[148:151], v[182:185], v[122:125]
	v_mfma_f32_16x16x32_bf16 v[110:113], v[140:143], v[190:193], v[110:113]
	v_mfma_f32_16x16x32_bf16 v[106:109], v[148:151], v[190:193], v[106:109]
	v_mfma_f32_16x16x32_bf16 v[94:97], v[140:143], v[198:201], v[94:97]
	v_mfma_f32_16x16x32_bf16 v[90:93], v[148:151], v[198:201], v[90:93]
	v_mfma_f32_16x16x32_bf16 v[78:81], v[140:143], v[206:209], v[78:81]
	v_mfma_f32_16x16x32_bf16 v[74:77], v[148:151], v[206:209], v[74:77]
	v_mfma_f32_16x16x32_bf16 v[126:129], v[144:147], v[186:189], v[126:129]
	v_mfma_f32_16x16x32_bf16 v[122:125], v[152:155], v[186:189], v[122:125]
	v_mfma_f32_16x16x32_bf16 v[110:113], v[144:147], v[194:197], v[110:113]
	v_mfma_f32_16x16x32_bf16 v[106:109], v[152:155], v[194:197], v[106:109]
	v_mfma_f32_16x16x32_bf16 v[94:97], v[144:147], v[202:205], v[94:97]
	v_mfma_f32_16x16x32_bf16 v[90:93], v[152:155], v[202:205], v[90:93]
	v_mfma_f32_16x16x32_bf16 v[78:81], v[144:147], v[230:233], v[78:81]
	v_mfma_f32_16x16x32_bf16 v[74:77], v[152:155], v[230:233], v[74:77]
	s_setprio 0
	s_setprio 1
	v_mfma_f32_16x16x32_bf16 v[118:121], v[156:159], v[182:185], v[118:121]
	v_mfma_f32_16x16x32_bf16 v[114:117], v[174:177], v[182:185], v[114:117]
	v_mfma_f32_16x16x32_bf16 v[102:105], v[156:159], v[190:193], v[102:105]
	v_mfma_f32_16x16x32_bf16 v[98:101], v[174:177], v[190:193], v[98:101]
	v_mfma_f32_16x16x32_bf16 v[86:89], v[156:159], v[198:201], v[86:89]
	v_mfma_f32_16x16x32_bf16 v[82:85], v[174:177], v[198:201], v[82:85]
	v_mfma_f32_16x16x32_bf16 v[70:73], v[156:159], v[206:209], v[70:73]
	v_mfma_f32_16x16x32_bf16 v[66:69], v[174:177], v[206:209], v[66:69]
	v_mfma_f32_16x16x32_bf16 v[118:121], v[170:173], v[186:189], v[118:121]
	v_mfma_f32_16x16x32_bf16 v[114:117], v[178:181], v[186:189], v[114:117]
	v_mfma_f32_16x16x32_bf16 v[102:105], v[170:173], v[194:197], v[102:105]
	v_mfma_f32_16x16x32_bf16 v[98:101], v[178:181], v[194:197], v[98:101]
	v_mfma_f32_16x16x32_bf16 v[86:89], v[170:173], v[202:205], v[86:89]
	v_mfma_f32_16x16x32_bf16 v[82:85], v[178:181], v[202:205], v[82:85]
	v_mfma_f32_16x16x32_bf16 v[70:73], v[170:173], v[230:233], v[70:73]
	v_mfma_f32_16x16x32_bf16 v[66:69], v[178:181], v[230:233], v[66:69]
	s_setprio 0
	s_barrier
; #define PG8_STAGE(bufoff, gbase, voff) do { _Pragma("unroll") for (int _i = 0; _i < 2; ++_i) \
;         __builtin_amdgcn_global_load_lds((const unsigned*)((const char*)(gbase) + (voff)[_i]), (PG8_LAS unsigned*)(lds + (bufoff) + ldsw + _i * 8192), 16, 0, 0); } while (0)
; #define PG8_LDA(dst, b, h) do { _Pragma("unroll") for (int m = 0; m < 4; ++m) _Pragma("unroll") for (int k = 0; k < 2; ++k) dst[m][k] = *(const PG8_LAS bf16x8*)(lds + PG8_SA(b, h) + aoff + m * 2048 + k * 1024); } while (0)
; #define PG8_MMA(ai, bj, At, Bt) do { __builtin_amdgcn_s_setprio(1); _Pragma("unroll") for (int m = 0; m < 4; ++m) _Pragma("unroll") for (int n = 0; n < 2; ++n) _Pragma("unroll") for (int k = 0; k < 2; ++k) \
;         acc[ai][bj][m][n] = __builtin_amdgcn_mfma_f32_16x16x32_bf16(Bt[n][k], At[m][k], acc[ai][bj][m][n], 0, 0, 0); __builtin_amdgcn_s_setprio(0); } while (0)
; #define PG8_WAIT_V(n) asm volatile("s_waitcnt vmcnt(" #n ")" ::: "memory")
; #define PG8_WAIT_L(n) asm volatile("s_waitcnt lgkmcnt(" #n ")" ::: "memory")
; #define PG8_BAR __builtin_amdgcn_s_barrier()
; #define PG8_SCHED __builtin_amdgcn_sched_barrier(0)
; template <class Epi, class Sched, bool ALIGN_EPI = false, bool SP2 = false>
; __device__ __forceinline__ void gemm_phase(PG8_LAS unsigned char* lds, const Gemm g, const Sched& S, const Epi& E) {
;     ...
;         for (int t = 0; t < nt; t += 2) {
;             const bool last = (t == nt - 2);
;             const char* a1 = cA + (size_t)(t + 1) * kstep;
;             const char* a2 = last ? nA : cA + (size_t)(t + 2) * kstep; const char* b2 = last ? nB : cB + (size_t)(t + 2) * kstep;
;             const char* a3 = a2 + kstep; const char* b3 = b2 + kstep;
;             if (last && has_next) S.a_ready(nxt);
;     ...
;             PG8_LDA(At, 1, 1); PG8_STAGE(PG8_SB(1, 0), b3, voffB); PG8_STAGE(PG8_SB(1, 1), b3 + hstep, voffB); PG8_STAGE(PG8_SA(1, 0), a3, voffA);
;             PG8_WAIT_V(8); PG8_WAIT_L(0); PG8_BAR; PG8_MMA(1, 0, At, B0); PG8_MMA(1, 1, At, B1); PG8_BAR; PG8_SCHED;
	s_add_i32 s16, s36, s65
	v_lshl_add_u64 v[210:211], v[210:211], 0, s[44:45]
	s_mov_b32 m0, s16
	ds_read_b128 v[182:185], v169 offset:49152
	ds_read_b128 v[186:189], v169 offset:50176
	ds_read_b128 v[190:193], v169 offset:51200
	ds_read_b128 v[194:197], v169 offset:52224
	ds_read_b128 v[198:201], v169 offset:53248
	ds_read_b128 v[202:205], v169 offset:54272
	ds_read_b128 v[206:209], v169 offset:55296
	ds_read_b128 v[230:233], v169 offset:56320
	global_load_lds_dwordx4 v[210:211], off
	v_lshl_add_u64 v[210:211], v[234:235], 0, s[44:45]
	s_add_i32 m0, s16, 0x2000
	s_add_i32 s16, s41, s65
	global_load_lds_dwordx4 v[210:211], off
	v_lshl_add_u64 v[210:211], v[236:237], 0, s[44:45]
	s_mov_b32 m0, s16
	s_nop 0
	global_load_lds_dwordx4 v[210:211], off
	v_lshl_add_u64 v[210:211], v[238:239], 0, s[44:45]
	s_add_i32 m0, s16, 0x2000
	s_nop 0
	global_load_lds_dwordx4 v[210:211], off
	v_lshl_add_u64 v[210:211], v[244:245], 0, s[44:45]
	s_mov_b32 m0, s73
	s_nop 0
	global_load_lds_dwordx4 v[210:211], off
	v_lshl_add_u64 v[210:211], v[246:247], 0, s[44:45]
	s_mov_b32 m0, s68
	s_nop 0
	global_load_lds_dwordx4 v[210:211], off
	s_waitcnt vmcnt(8)
	s_waitcnt lgkmcnt(0)
	s_barrier
	s_setprio 1
	s_waitcnt lgkmcnt(0)
	v_mfma_f32_16x16x32_bf16 v[60:63], v[140:143], v[182:185], v[60:63]
	v_mfma_f32_16x16x32_bf16 v[56:59], v[148:151], v[182:185], v[56:59]
	v_mfma_f32_16x16x32_bf16 v[44:47], v[140:143], v[190:193], v[44:47]
	v_mfma_f32_16x16x32_bf16 v[40:43], v[148:151], v[190:193], v[40:43]
	v_mfma_f32_16x16x32_bf16 v[28:31], v[140:143], v[198:201], v[28:31]
	v_mfma_f32_16x16x32_bf16 v[24:27], v[148:151], v[198:201], v[24:27]
	v_mfma_f32_16x16x32_bf16 v[12:15], v[140:143], v[206:209], v[12:15]
	v_mfma_f32_16x16x32_bf16 v[8:11], v[148:151], v[206:209], v[8:11]
	v_mfma_f32_16x16x32_bf16 v[60:63], v[144:147], v[186:189], v[60:63]
	v_mfma_f32_16x16x32_bf16 v[56:59], v[152:155], v[186:189], v[56:59]
	v_mfma_f32_16x16x32_bf16 v[44:47], v[144:147], v[194:197], v[44:47]
	v_mfma_f32_16x16x32_bf16 v[40:43], v[152:155], v[194:197], v[40:43]
	v_mfma_f32_16x16x32_bf16 v[28:31], v[144:147], v[202:205], v[28:31]
	v_mfma_f32_16x16x32_bf16 v[24:27], v[152:155], v[202:205], v[24:27]
	v_mfma_f32_16x16x32_bf16 v[12:15], v[144:147], v[230:233], v[12:15]
	v_mfma_f32_16x16x32_bf16 v[8:11], v[152:155], v[230:233], v[8:11]
	s_setprio 0
	s_setprio 1
	v_mfma_f32_16x16x32_bf16 v[52:55], v[156:159], v[182:185], v[52:55]
	v_mfma_f32_16x16x32_bf16 v[48:51], v[174:177], v[182:185], v[48:51]
	v_mfma_f32_16x16x32_bf16 v[36:39], v[156:159], v[190:193], v[36:39]
	v_mfma_f32_16x16x32_bf16 v[32:35], v[174:177], v[190:193], v[32:35]
	v_mfma_f32_16x16x32_bf16 v[20:23], v[156:159], v[198:201], v[20:23]
	v_mfma_f32_16x16x32_bf16 v[16:19], v[174:177], v[198:201], v[16:19]
	v_mfma_f32_16x16x32_bf16 v[4:7], v[156:159], v[206:209], v[4:7]
	v_mfma_f32_16x16x32_bf16 v[0:3], v[174:177], v[206:209], v[0:3]
	v_mfma_f32_16x16x32_bf16 v[52:55], v[170:173], v[186:189], v[52:55]
	v_mfma_f32_16x16x32_bf16 v[48:51], v[178:181], v[186:189], v[48:51]
	v_mfma_f32_16x16x32_bf16 v[36:39], v[170:173], v[194:197], v[36:39]
	v_mfma_f32_16x16x32_bf16 v[32:35], v[178:181], v[194:197], v[32:35]
	v_mfma_f32_16x16x32_bf16 v[20:23], v[170:173], v[202:205], v[20:23]
	v_mfma_f32_16x16x32_bf16 v[16:19], v[178:181], v[202:205], v[16:19]
	v_mfma_f32_16x16x32_bf16 v[4:7], v[170:173], v[230:233], v[4:7]
	v_mfma_f32_16x16x32_bf16 v[0:3], v[178:181], v[230:233], v[0:3]
	s_setprio 0
	s_add_u32 s8, s8, 0x100
	s_addc_u32 s9, s9, 0
	s_add_u32 s27, s27, 0x100
	s_addc_u32 s30, s30, 0
	s_cmp_ge_u32 s31, s87
	s_mov_b32 s16, s31
	s_cbranch_scc1 .Lk_exit_a
	s_add_i32 s31, s16, 2
	s_add_u32 s36, s8, 0x80
	s_addc_u32 s17, s9, 0
	s_add_i32 s41, 0, 0x10000
	s_cmp_eq_u32 s72, s16
	s_cselect_b32 s17, s1, s17
	s_cselect_b32 s16, s0, s36
	s_cselect_b32 vcc_hi, s93, s30
	s_cselect_b32 vcc_lo, s92, s27
	s_add_i32 s36, 0, 0x14000
	v_add_u32_e32 v152, s41, v161
	v_add_u32_e32 v178, s36, v161
	s_barrier
	s_branch .Lk_body
.Lk_exit_a:
	s_barrier
	s_branch .Lk_loop_done

; #define PG8_STAGE(bufoff, gbase, voff) do { _Pragma("unroll") for (int _i = 0; _i < 2; ++_i) \
;         __builtin_amdgcn_global_load_lds((const unsigned*)((const char*)(gbase) + (voff)[_i]), (PG8_LAS unsigned*)(lds + (bufoff) + ldsw + _i * 8192), 16, 0, 0); } while (0)
; #define PG8_LDA(dst, b, h) do { _Pragma("unroll") for (int m = 0; m < 4; ++m) _Pragma("unroll") for (int k = 0; k < 2; ++k) dst[m][k] = *(const PG8_LAS bf16x8*)(lds + PG8_SA(b, h) + aoff + m * 2048 + k * 1024); } while (0)
; #define PG8_LDB(dst, b, h) do { _Pragma("unroll") for (int n = 0; n < 2; ++n) _Pragma("unroll") for (int k = 0; k < 2; ++k) dst[n][k] = *(const PG8_LAS bf16x8*)(lds + PG8_SB(b, h) + boff + n * 2048 + k * 1024); } while (0)
; #define PG8_MMA(ai, bj, At, Bt) do { __builtin_amdgcn_s_setprio(1); _Pragma("unroll") for (int m = 0; m < 4; ++m) _Pragma("unroll") for (int n = 0; n < 2; ++n) _Pragma("unroll") for (int k = 0; k < 2; ++k) \
;         acc[ai][bj][m][n] = __builtin_amdgcn_mfma_f32_16x16x32_bf16(Bt[n][k], At[m][k], acc[ai][bj][m][n], 0, 0, 0); __builtin_amdgcn_s_setprio(0); } while (0)
; #define PG8_WAIT_V(n) asm volatile("s_waitcnt vmcnt(" #n ")" ::: "memory")
; #define PG8_WAIT_L(n) asm volatile("s_waitcnt lgkmcnt(" #n ")" ::: "memory")
; #define PG8_BAR __builtin_amdgcn_s_barrier()
; #define PG8_SCHED __builtin_amdgcn_sched_barrier(0)
; template <class Epi, class Sched, bool ALIGN_EPI = false, bool SP2 = false>
; __device__ __forceinline__ void gemm_phase(PG8_LAS unsigned char* lds, const Gemm g, const Sched& S, const Epi& E) {
;     ...
;             PG8_LDB(B0, 0, 0); PG8_LDB(B1, 0, 1); PG8_SCHED; PG8_LDA(At, 0, 0); PG8_STAGE(PG8_SA(1, 1), a1 + hstep, voffA);
;             PG8_WAIT_V(8); PG8_WAIT_L(0); PG8_BAR; PG8_MMA(0, 0, At, B0); PG8_MMA(0, 1, At, B1); PG8_BAR; PG8_SCHED;
;             PG8_LDA(At, 0, 1); PG8_STAGE(PG8_SB(0, 0), b2, voffB); PG8_STAGE(PG8_SB(0, 1), b2 + hstep, voffB); PG8_STAGE(PG8_SA(0, 0), a2, voffA);
;             PG8_WAIT_V(8); PG8_WAIT_L(0); PG8_BAR; PG8_MMA(1, 0, At, B0); PG8_MMA(1, 1, At, B1); PG8_BAR; PG8_SCHED;
.Lk_body:
	ds_read_b128 v[140:143], v152
	ds_read_b128 v[144:147], v152 offset:1024
	ds_read_b128 v[148:151], v152 offset:2048
	ds_read_b128 v[152:155], v152 offset:3072
	ds_read_b128 v[156:159], v178
	ds_read_b128 v[170:173], v178 offset:1024
	ds_read_b128 v[174:177], v178 offset:2048
	ds_read_b128 v[178:181], v178 offset:3072
	v_lshl_add_u64 v[210:211], s[8:9], 0, v[136:137]
	s_add_i32 m0, s76, 0xc000
	ds_read_b128 v[182:185], v169
	ds_read_b128 v[186:189], v169 offset:1024
	ds_read_b128 v[190:193], v169 offset:2048
	ds_read_b128 v[194:197], v169 offset:3072
	ds_read_b128 v[198:201], v169 offset:4096
	ds_read_b128 v[202:205], v169 offset:5120
	ds_read_b128 v[206:209], v169 offset:6144
	ds_read_b128 v[230:233], v169 offset:7168
	global_load_lds_dwordx4 v[210:211], off
	v_lshl_add_u64 v[210:211], s[8:9], 0, v[138:139]
	s_add_i32 m0, s76, 0xe000
	s_nop 0
	global_load_lds_dwordx4 v[210:211], off
	s_waitcnt vmcnt(8)
	s_waitcnt lgkmcnt(0)
	s_barrier
	s_setprio 1
	s_waitcnt lgkmcnt(0)
	v_mfma_f32_16x16x32_bf16 v[126:129], v[140:143], v[182:185], v[126:129]
	v_mfma_f32_16x16x32_bf16 v[122:125], v[148:151], v[182:185], v[122:125]
	v_mfma_f32_16x16x32_bf16 v[110:113], v[140:143], v[190:193], v[110:113]
	v_mfma_f32_16x16x32_bf16 v[106:109], v[148:151], v[190:193], v[106:109]
	v_mfma_f32_16x16x32_bf16 v[94:97], v[140:143], v[198:201], v[94:97]
	v_mfma_f32_16x16x32_bf16 v[90:93], v[148:151], v[198:201], v[90:93]
	v_mfma_f32_16x16x32_bf16 v[78:81], v[140:143], v[206:209], v[78:81]
	v_mfma_f32_16x16x32_bf16 v[74:77], v[148:151], v[206:209], v[74:77]
	v_mfma_f32_16x16x32_bf16 v[126:129], v[144:147], v[186:189], v[126:129]
	v_mfma_f32_16x16x32_bf16 v[122:125], v[152:155], v[186:189], v[122:125]
	v_mfma_f32_16x16x32_bf16 v[110:113], v[144:147], v[194:197], v[110:113]
	v_mfma_f32_16x16x32_bf16 v[106:109], v[152:155], v[194:197], v[106:109]
	v_mfma_f32_16x16x32_bf16 v[94:97], v[144:147], v[202:205], v[94:97]
	v_mfma_f32_16x16x32_bf16 v[90:93], v[152:155], v[202:205], v[90:93]
	v_mfma_f32_16x16x32_bf16 v[78:81], v[144:147], v[230:233], v[78:81]
	v_mfma_f32_16x16x32_bf16 v[74:77], v[152:155], v[230:233], v[74:77]
	s_setprio 0
	s_setprio 1
	v_mfma_f32_16x16x32_bf16 v[118:121], v[156:159], v[182:185], v[118:121]
	v_mfma_f32_16x16x32_bf16 v[114:117], v[174:177], v[182:185], v[114:117]
	v_mfma_f32_16x16x32_bf16 v[102:105], v[156:159], v[190:193], v[102:105]
	v_mfma_f32_16x16x32_bf16 v[98:101], v[174:177], v[190:193], v[98:101]
	v_mfma_f32_16x16x32_bf16 v[86:89], v[156:159], v[198:201], v[86:89]
	v_mfma_f32_16x16x32_bf16 v[82:85], v[174:177], v[198:201], v[82:85]
	v_mfma_f32_16x16x32_bf16 v[70:73], v[156:159], v[206:209], v[70:73]
	v_mfma_f32_16x16x32_bf16 v[66:69], v[174:177], v[206:209], v[66:69]
	v_mfma_f32_16x16x32_bf16 v[118:121], v[170:173], v[186:189], v[118:121]
	v_mfma_f32_16x16x32_bf16 v[114:117], v[178:181], v[186:189], v[114:117]
	v_mfma_f32_16x16x32_bf16 v[102:105], v[170:173], v[194:197], v[102:105]
	v_mfma_f32_16x16x32_bf16 v[98:101], v[178:181], v[194:197], v[98:101]
	v_mfma_f32_16x16x32_bf16 v[86:89], v[170:173], v[202:205], v[86:89]
	v_mfma_f32_16x16x32_bf16 v[82:85], v[178:181], v[202:205], v[82:85]
	v_mfma_f32_16x16x32_bf16 v[70:73], v[170:173], v[230:233], v[70:73]
	v_mfma_f32_16x16x32_bf16 v[66:69], v[178:181], v[230:233], v[66:69]
	s_setprio 0
	s_barrier
	s_add_i32 s41, s41, s65
	v_lshl_add_u64 v[210:211], vcc, 0, v[64:65]
	s_mov_b32 m0, s41
	ds_read_b128 v[182:185], v169 offset:16384
	ds_read_b128 v[186:189], v169 offset:17408
	ds_read_b128 v[190:193], v169 offset:18432
	ds_read_b128 v[194:197], v169 offset:19456
	ds_read_b128 v[198:201], v169 offset:20480
	ds_read_b128 v[202:205], v169 offset:21504
	ds_read_b128 v[206:209], v169 offset:22528
	ds_read_b128 v[230:233], v169 offset:23552
	global_load_lds_dwordx4 v[210:211], off
	s_add_i32 m0, s41, 0x2000
	v_lshl_add_u64 v[234:235], vcc, 0, v[134:135]
	s_add_u32 vcc_lo, vcc_lo, s4
	s_addc_u32 vcc_hi, vcc_hi, 0
	s_add_i32 s36, s36, s65
	global_load_lds_dwordx4 v[234:235], off
	v_lshl_add_u64 v[236:237], vcc, 0, v[64:65]
	s_mov_b32 m0, s36
	v_lshl_add_u64 v[238:239], vcc, 0, v[134:135]
	global_load_lds_dwordx4 v[236:237], off
	s_add_i32 m0, s36, 0x2000
	v_lshl_add_u64 v[244:245], s[16:17], 0, v[130:131]
	global_load_lds_dwordx4 v[238:239], off
	s_mov_b32 m0, s76
	v_lshl_add_u64 v[246:247], s[16:17], 0, v[132:133]
	global_load_lds_dwordx4 v[244:245], off
	s_mov_b32 m0, s2
	s_nop 0
	global_load_lds_dwordx4 v[246:247], off
	s_waitcnt vmcnt(8)
	s_waitcnt lgkmcnt(0)
	s_barrier
	s_setprio 1
	s_waitcnt lgkmcnt(0)
	v_mfma_f32_16x16x32_bf16 v[60:63], v[140:143], v[182:185], v[60:63]
	v_mfma_f32_16x16x32_bf16 v[56:59], v[148:151], v[182:185], v[56:59]
	v_mfma_f32_16x16x32_bf16 v[44:47], v[140:143], v[190:193], v[44:47]
	v_mfma_f32_16x16x32_bf16 v[40:43], v[148:151], v[190:193], v[40:43]
	v_mfma_f32_16x16x32_bf16 v[28:31], v[140:143], v[198:201], v[28:31]
	v_mfma_f32_16x16x32_bf16 v[24:27], v[148:151], v[198:201], v[24:27]
	v_mfma_f32_16x16x32_bf16 v[12:15], v[140:143], v[206:209], v[12:15]
	v_mfma_f32_16x16x32_bf16 v[8:11], v[148:151], v[206:209], v[8:11]
	v_mfma_f32_16x16x32_bf16 v[60:63], v[144:147], v[186:189], v[60:63]
	v_mfma_f32_16x16x32_bf16 v[56:59], v[152:155], v[186:189], v[56:59]
	v_mfma_f32_16x16x32_bf16 v[44:47], v[144:147], v[194:197], v[44:47]
	v_mfma_f32_16x16x32_bf16 v[40:43], v[152:155], v[194:197], v[40:43]
	v_mfma_f32_16x16x32_bf16 v[28:31], v[144:147], v[202:205], v[28:31]
	v_mfma_f32_16x16x32_bf16 v[24:27], v[152:155], v[202:205], v[24:27]
	v_mfma_f32_16x16x32_bf16 v[12:15], v[144:147], v[230:233], v[12:15]
	v_mfma_f32_16x16x32_bf16 v[8:11], v[152:155], v[230:233], v[8:11]
	s_setprio 0
	s_setprio 1
	v_mfma_f32_16x16x32_bf16 v[52:55], v[156:159], v[182:185], v[52:55]
	v_mfma_f32_16x16x32_bf16 v[48:51], v[174:177], v[182:185], v[48:51]
	v_mfma_f32_16x16x32_bf16 v[36:39], v[156:159], v[190:193], v[36:39]
	v_mfma_f32_16x16x32_bf16 v[32:35], v[174:177], v[190:193], v[32:35]
	v_mfma_f32_16x16x32_bf16 v[20:23], v[156:159], v[198:201], v[20:23]
	v_mfma_f32_16x16x32_bf16 v[16:19], v[174:177], v[198:201], v[16:19]
	v_mfma_f32_16x16x32_bf16 v[4:7], v[156:159], v[206:209], v[4:7]
	v_mfma_f32_16x16x32_bf16 v[0:3], v[174:177], v[206:209], v[0:3]
	v_mfma_f32_16x16x32_bf16 v[52:55], v[170:173], v[186:189], v[52:55]
	v_mfma_f32_16x16x32_bf16 v[48:51], v[178:181], v[186:189], v[48:51]
	v_mfma_f32_16x16x32_bf16 v[36:39], v[170:173], v[194:197], v[36:39]
	v_mfma_f32_16x16x32_bf16 v[32:35], v[178:181], v[194:197], v[32:35]
	v_mfma_f32_16x16x32_bf16 v[20:23], v[170:173], v[202:205], v[20:23]
	v_mfma_f32_16x16x32_bf16 v[16:19], v[178:181], v[202:205], v[16:19]
	v_mfma_f32_16x16x32_bf16 v[4:7], v[170:173], v[230:233], v[4:7]
	v_mfma_f32_16x16x32_bf16 v[0:3], v[178:181], v[230:233], v[0:3]
	s_setprio 0
	s_barrier
; #define PG8_STAGE(bufoff, gbase, voff) do { _Pragma("unroll") for (int _i = 0; _i < 2; ++_i) \
;         __builtin_amdgcn_global_load_lds((const unsigned*)((const char*)(gbase) + (voff)[_i]), (PG8_LAS unsigned*)(lds + (bufoff) + ldsw + _i * 8192), 16, 0, 0); } while (0)
; #define PG8_LDA(dst, b, h) do { _Pragma("unroll") for (int m = 0; m < 4; ++m) _Pragma("unroll") for (int k = 0; k < 2; ++k) dst[m][k] = *(const PG8_LAS bf16x8*)(lds + PG8_SA(b, h) + aoff + m * 2048 + k * 1024); } while (0)
; #define PG8_LDB(dst, b, h) do { _Pragma("unroll") for (int n = 0; n < 2; ++n) _Pragma("unroll") for (int k = 0; k < 2; ++k) dst[n][k] = *(const PG8_LAS bf16x8*)(lds + PG8_SB(b, h) + boff + n * 2048 + k * 1024); } while (0)
; #define PG8_MMA(ai, bj, At, Bt) do { __builtin_amdgcn_s_setprio(1); _Pragma("unroll") for (int m = 0; m < 4; ++m) _Pragma("unroll") for (int n = 0; n < 2; ++n) _Pragma("unroll") for (int k = 0; k < 2; ++k) \
;         acc[ai][bj][m][n] = __builtin_amdgcn_mfma_f32_16x16x32_bf16(Bt[n][k], At[m][k], acc[ai][bj][m][n], 0, 0, 0); __builtin_amdgcn_s_setprio(0); } while (0)
; #define PG8_WAIT_V(n) asm volatile("s_waitcnt vmcnt(" #n ")" ::: "memory")
; #define PG8_WAIT_L(n) asm volatile("s_waitcnt lgkmcnt(" #n ")" ::: "memory")
; #define PG8_BAR __builtin_amdgcn_s_barrier()
; #define PG8_SCHED __builtin_amdgcn_sched_barrier(0)
; template <class Epi, class Sched, bool ALIGN_EPI = false, bool SP2 = false>
; __device__ __forceinline__ void gemm_phase(PG8_LAS unsigned char* lds, const Gemm g, const Sched& S, const Epi& E) {
;     ...
;             PG8_LDB(B0, 1, 0); PG8_LDB(B1, 1, 1); PG8_SCHED; PG8_LDA(At, 1, 0); PG8_STAGE(PG8_SA(0, 1), a2 + hstep, voffA);
;             PG8_WAIT_V(8); PG8_WAIT_L(0); PG8_BAR; PG8_MMA(0, 0, At, B0); PG8_MMA(0, 1, At, B1); PG8_BAR; PG8_SCHED;
	s_add_i32 s36, 0, 0x18000
	s_add_i32 s41, 0, 0x1c000
	v_add_u32_e32 v152, s36, v161
	v_add_u32_e32 v178, s41, v161
	ds_read_b128 v[140:143], v152
	ds_read_b128 v[144:147], v152 offset:1024
	ds_read_b128 v[148:151], v152 offset:2048
	ds_read_b128 v[152:155], v152 offset:3072
	ds_read_b128 v[156:159], v178
	ds_read_b128 v[170:173], v178 offset:1024
	ds_read_b128 v[174:177], v178 offset:2048
	ds_read_b128 v[178:181], v178 offset:3072
	s_add_u32 s16, s16, s4
	s_addc_u32 s17, s17, 0
	s_mov_b32 m0, s3
	v_lshl_add_u64 v[248:249], s[16:17], 0, v[130:131]
	ds_read_b128 v[182:185], v169 offset:32768
	ds_read_b128 v[186:189], v169 offset:33792
	ds_read_b128 v[190:193], v169 offset:34816
	ds_read_b128 v[194:197], v169 offset:35840
	ds_read_b128 v[198:201], v169 offset:36864
	ds_read_b128 v[202:205], v169 offset:37888
	ds_read_b128 v[206:209], v169 offset:38912
	ds_read_b128 v[230:233], v169 offset:39936
	global_load_lds_dwordx4 v[248:249], off
	v_lshl_add_u64 v[248:249], s[16:17], 0, v[132:133]
	s_mov_b32 m0, s70
	s_nop 0
	global_load_lds_dwordx4 v[248:249], off
	s_waitcnt vmcnt(8)
	s_waitcnt lgkmcnt(0)
	s_barrier
	s_setprio 1
	s_waitcnt lgkmcnt(0)
	v_mfma_f32_16x16x32_bf16 v[126:129], v[140:143], v[182:185], v[126:129]
	v_mfma_f32_16x16x32_bf16 v[122:125], v[148:151], v[182:185], v[122:125]
	v_mfma_f32_16x16x32_bf16 v[110:113], v[140:143], v[190:193], v[110:113]
	v_mfma_f32_16x16x32_bf16 v[106:109], v[148:151], v[190:193], v[106:109]
	v_mfma_f32_16x16x32_bf16 v[94:97], v[140:143], v[198:201], v[94:97]
	v_mfma_f32_16x16x32_bf16 v[90:93], v[148:151], v[198:201], v[90:93]
	v_mfma_f32_16x16x32_bf16 v[78:81], v[140:143], v[206:209], v[78:81]
	v_mfma_f32_16x16x32_bf16 v[74:77], v[148:151], v[206:209], v[74:77]
	v_mfma_f32_16x16x32_bf16 v[126:129], v[144:147], v[186:189], v[126:129]
	v_mfma_f32_16x16x32_bf16 v[122:125], v[152:155], v[186:189], v[122:125]
	v_mfma_f32_16x16x32_bf16 v[110:113], v[144:147], v[194:197], v[110:113]
	v_mfma_f32_16x16x32_bf16 v[106:109], v[152:155], v[194:197], v[106:109]
	v_mfma_f32_16x16x32_bf16 v[94:97], v[144:147], v[202:205], v[94:97]
	v_mfma_f32_16x16x32_bf16 v[90:93], v[152:155], v[202:205], v[90:93]
	v_mfma_f32_16x16x32_bf16 v[78:81], v[144:147], v[230:233], v[78:81]
	v_mfma_f32_16x16x32_bf16 v[74:77], v[152:155], v[230:233], v[74:77]
	s_setprio 0
	s_setprio 1
	v_mfma_f32_16x16x32_bf16 v[118:121], v[156:159], v[182:185], v[118:121]
	v_mfma_f32_16x16x32_bf16 v[114:117], v[174:177], v[182:185], v[114:117]
	v_mfma_f32_16x16x32_bf16 v[102:105], v[156:159], v[190:193], v[102:105]
	v_mfma_f32_16x16x32_bf16 v[98:101], v[174:177], v[190:193], v[98:101]
	v_mfma_f32_16x16x32_bf16 v[86:89], v[156:159], v[198:201], v[86:89]
	v_mfma_f32_16x16x32_bf16 v[82:85], v[174:177], v[198:201], v[82:85]
	v_mfma_f32_16x16x32_bf16 v[70:73], v[156:159], v[206:209], v[70:73]
	v_mfma_f32_16x16x32_bf16 v[66:69], v[174:177], v[206:209], v[66:69]
	v_mfma_f32_16x16x32_bf16 v[118:121], v[170:173], v[186:189], v[118:121]
	v_mfma_f32_16x16x32_bf16 v[114:117], v[178:181], v[186:189], v[114:117]
	v_mfma_f32_16x16x32_bf16 v[102:105], v[170:173], v[194:197], v[102:105]
	v_mfma_f32_16x16x32_bf16 v[98:101], v[178:181], v[194:197], v[98:101]
	v_mfma_f32_16x16x32_bf16 v[86:89], v[170:173], v[202:205], v[86:89]
	v_mfma_f32_16x16x32_bf16 v[82:85], v[178:181], v[202:205], v[82:85]
	v_mfma_f32_16x16x32_bf16 v[70:73], v[170:173], v[230:233], v[70:73]
	v_mfma_f32_16x16x32_bf16 v[66:69], v[178:181], v[230:233], v[66:69]
	s_setprio 0
	s_barrier
; #define PG8_STAGE(bufoff, gbase, voff) do { _Pragma("unroll") for (int _i = 0; _i < 2; ++_i) \
;         __builtin_amdgcn_global_load_lds((const unsigned*)((const char*)(gbase) + (voff)[_i]), (PG8_LAS unsigned*)(lds + (bufoff) + ldsw + _i * 8192), 16, 0, 0); } while (0)
; #define PG8_LDA(dst, b, h) do { _Pragma("unroll") for (int m = 0; m < 4; ++m) _Pragma("unroll") for (int k = 0; k < 2; ++k) dst[m][k] = *(const PG8_LAS bf16x8*)(lds + PG8_SA(b, h) + aoff + m * 2048 + k * 1024); } while (0)
; #define PG8_MMA(ai, bj, At, Bt) do { __builtin_amdgcn_s_setprio(1); _Pragma("unroll") for (int m = 0; m < 4; ++m) _Pragma("unroll") for (int n = 0; n < 2; ++n) _Pragma("unroll") for (int k = 0; k < 2; ++k) \
;         acc[ai][bj][m][n] = __builtin_amdgcn_mfma_f32_16x16x32_bf16(Bt[n][k], At[m][k], acc[ai][bj][m][n], 0, 0, 0); __builtin_amdgcn_s_setprio(0); } while (0)
; #define PG8_WAIT_V(n) asm volatile("s_waitcnt vmcnt(" #n ")" ::: "memory")
; #define PG8_WAIT_L(n) asm volatile("s_waitcnt lgkmcnt(" #n ")" ::: "memory")
; #define PG8_BAR __builtin_amdgcn_s_barrier()
; #define PG8_SCHED __builtin_amdgcn_sched_barrier(0)
;     __device__ __forceinline__ void operator()(const f32x4 (&acc)[2][2][4][2], const Unit& u, int wr, int wc, int fr, int fq) const {
;     ...
;         } else if (k == EK_Q) {
;             k = EK_PLAIN; if (u.pn >= 4) { ob = WS_QR; colt = (u.pn - 4) * 256; ld = 512; }
; template <class Epi, class Sched, bool ALIGN_EPI = false, bool SP2 = false>
; __device__ __forceinline__ void gemm_phase(PG8_LAS unsigned char* lds, const Gemm g, const Sched& S, const Epi& E) {
;     ...
;             PG8_LDA(At, 1, 1); PG8_STAGE(PG8_SB(1, 0), b3, voffB); PG8_STAGE(PG8_SB(1, 1), b3 + hstep, voffB); PG8_STAGE(PG8_SA(1, 0), a3, voffA);
;             PG8_WAIT_V(8); PG8_WAIT_L(0); PG8_BAR; PG8_MMA(1, 0, At, B0); PG8_MMA(1, 1, At, B1); PG8_BAR; PG8_SCHED;
	s_add_i32 s16, s36, s65
	v_lshl_add_u64 v[210:211], v[210:211], 0, s[44:45]
	s_mov_b32 m0, s16
	ds_read_b128 v[182:185], v169 offset:49152
	ds_read_b128 v[186:189], v169 offset:50176
	ds_read_b128 v[190:193], v169 offset:51200
	ds_read_b128 v[194:197], v169 offset:52224
	ds_read_b128 v[198:201], v169 offset:53248
	ds_read_b128 v[202:205], v169 offset:54272
	ds_read_b128 v[206:209], v169 offset:55296
	ds_read_b128 v[230:233], v169 offset:56320
	global_load_lds_dwordx4 v[210:211], off
	v_lshl_add_u64 v[210:211], v[234:235], 0, s[44:45]
	s_add_i32 m0, s16, 0x2000
	s_add_i32 s16, s41, s65
	global_load_lds_dwordx4 v[210:211], off
	v_lshl_add_u64 v[210:211], v[236:237], 0, s[44:45]
	s_mov_b32 m0, s16
	s_nop 0
	global_load_lds_dwordx4 v[210:211], off
	v_lshl_add_u64 v[210:211], v[238:239], 0, s[44:45]
	s_add_i32 m0, s16, 0x2000
	s_nop 0
	global_load_lds_dwordx4 v[210:211], off
	v_lshl_add_u64 v[210:211], v[244:245], 0, s[44:45]
	s_mov_b32 m0, s73
	s_nop 0
	global_load_lds_dwordx4 v[210:211], off
	v_lshl_add_u64 v[210:211], v[246:247], 0, s[44:45]
	s_mov_b32 m0, s68
	s_nop 0
	global_load_lds_dwordx4 v[210:211], off
	s_waitcnt vmcnt(8)
	s_waitcnt lgkmcnt(0)
	s_barrier
	s_setprio 1
	s_waitcnt lgkmcnt(0)
	v_mfma_f32_16x16x32_bf16 v[60:63], v[140:143], v[182:185], v[60:63]
	v_mfma_f32_16x16x32_bf16 v[56:59], v[148:151], v[182:185], v[56:59]
	v_mfma_f32_16x16x32_bf16 v[44:47], v[140:143], v[190:193], v[44:47]
	v_mfma_f32_16x16x32_bf16 v[40:43], v[148:151], v[190:193], v[40:43]
	v_mfma_f32_16x16x32_bf16 v[28:31], v[140:143], v[198:201], v[28:31]
	v_mfma_f32_16x16x32_bf16 v[24:27], v[148:151], v[198:201], v[24:27]
	v_mfma_f32_16x16x32_bf16 v[12:15], v[140:143], v[206:209], v[12:15]
	v_mfma_f32_16x16x32_bf16 v[8:11], v[148:151], v[206:209], v[8:11]
	v_mfma_f32_16x16x32_bf16 v[60:63], v[144:147], v[186:189], v[60:63]
	v_mfma_f32_16x16x32_bf16 v[56:59], v[152:155], v[186:189], v[56:59]
	v_mfma_f32_16x16x32_bf16 v[44:47], v[144:147], v[194:197], v[44:47]
	v_mfma_f32_16x16x32_bf16 v[40:43], v[152:155], v[194:197], v[40:43]
	v_mfma_f32_16x16x32_bf16 v[28:31], v[144:147], v[202:205], v[28:31]
	v_mfma_f32_16x16x32_bf16 v[24:27], v[152:155], v[202:205], v[24:27]
	v_mfma_f32_16x16x32_bf16 v[12:15], v[144:147], v[230:233], v[12:15]
	v_mfma_f32_16x16x32_bf16 v[8:11], v[152:155], v[230:233], v[8:11]
	s_setprio 0
	s_setprio 1
	v_mfma_f32_16x16x32_bf16 v[52:55], v[156:159], v[182:185], v[52:55]
	v_mfma_f32_16x16x32_bf16 v[48:51], v[174:177], v[182:185], v[48:51]
	v_mfma_f32_16x16x32_bf16 v[36:39], v[156:159], v[190:193], v[36:39]
	v_mfma_f32_16x16x32_bf16 v[32:35], v[174:177], v[190:193], v[32:35]
	v_mfma_f32_16x16x32_bf16 v[20:23], v[156:159], v[198:201], v[20:23]
	v_mfma_f32_16x16x32_bf16 v[16:19], v[174:177], v[198:201], v[16:19]
	v_mfma_f32_16x16x32_bf16 v[4:7], v[156:159], v[206:209], v[4:7]
	v_mfma_f32_16x16x32_bf16 v[0:3], v[174:177], v[206:209], v[0:3]
	v_mfma_f32_16x16x32_bf16 v[52:55], v[170:173], v[186:189], v[52:55]
	v_mfma_f32_16x16x32_bf16 v[48:51], v[178:181], v[186:189], v[48:51]
	v_mfma_f32_16x16x32_bf16 v[36:39], v[170:173], v[194:197], v[36:39]
	v_mfma_f32_16x16x32_bf16 v[32:35], v[178:181], v[194:197], v[32:35]
	v_mfma_f32_16x16x32_bf16 v[20:23], v[170:173], v[202:205], v[20:23]
	v_mfma_f32_16x16x32_bf16 v[16:19], v[178:181], v[202:205], v[16:19]
	v_mfma_f32_16x16x32_bf16 v[4:7], v[170:173], v[230:233], v[4:7]
	v_mfma_f32_16x16x32_bf16 v[0:3], v[178:181], v[230:233], v[0:3]
	s_setprio 0
	s_add_u32 s8, s8, 0x100
	s_addc_u32 s9, s9, 0
	s_add_u32 s27, s27, 0x100
	s_addc_u32 s30, s30, 0
	s_cmp_ge_u32 s31, s87
	s_mov_b32 s16, s31
	s_cbranch_scc1 .Lk_exit_b
	s_add_i32 s31, s16, 2
	s_add_u32 s36, s8, 0x80
	s_addc_u32 s17, s9, 0
	s_add_i32 s41, 0, 0x10000
	s_cmp_eq_u32 s72, s16
	s_cselect_b32 s17, s1, s17
	s_cselect_b32 s16, s0, s36
	s_cselect_b32 vcc_hi, s93, s30
	s_cselect_b32 vcc_lo, s92, s27
	s_add_i32 s36, 0, 0x14000
	v_add_u32_e32 v152, s41, v161
	v_add_u32_e32 v178, s36, v161
	s_barrier
	s_branch .Lk_body
.Lk_exit_b:
	s_barrier
.Lk_loop_done:
.LBB0_691:
	s_lshl_b32 s30, s40, 8
	s_cmp_gt_i32 s24, 6
	s_mov_b64 s[16:17], -1
	s_cbranch_scc0 .LBB0_695
	s_cmp_lt_i32 s40, 4
	s_mov_b64 s[8:9], s[88:89]
	s_mov_b32 s27, s37
	s_mov_b32 s31, s30
	s_cbranch_scc1 .LBB0_694
	s_add_i32 s31, s30, 0xfffffc00
	s_movk_i32 s27, 0x200
	s_mov_b64 s[8:9], 0x10a00000
